# NSA importance reduction via DPP instead of ds_bpermute (pass B)
# speedup vs baseline: 1.0570x; 1.0033x over previous
.LBB0_1955:
	v_exp_f32_e32 v42, v138
	v_exp_f32_e32 v43, v141
	v_exp_f32_e32 v44, v139
	v_exp_f32_e32 v45, v140
	v_mul_f32_e32 v46, v146, v43
	v_add_f32_e32 v47, v42, v44
	v_add_f32_e32 v47, v45, v47
	v_mul_f32_e32 v48, 0.5, v46
	v_fma_f32 v47, v146, v47, v48
	s_nop 1
	v_add_f32_dpp v48, v48, v48 quad_perm:[1,0,3,2] row_mask:0xf bank_mask:0xf
	v_add_f32_dpp v47, v47, v47 quad_perm:[1,0,3,2] row_mask:0xf bank_mask:0xf
	s_nop 0
	v_add_f32_dpp v48, v48, v48 quad_perm:[2,3,0,1] row_mask:0xf bank_mask:0xf
	v_add_f32_dpp v47, v47, v47 quad_perm:[2,3,0,1] row_mask:0xf bank_mask:0xf
	s_nop 0
	v_add_f32_dpp v48, v48, v48 row_half_mirror row_mask:0xf bank_mask:0xf
	v_add_f32_dpp v47, v47, v47 row_half_mirror row_mask:0xf bank_mask:0xf
	s_and_saveexec_b64 s[20:21], s[4:5]
	ds_add_f32 v147, v47
	ds_add_f32 v147, v48 offset:4
	s_or_b64 exec, exec, s[20:21]
	v_exp_f32_e32 v49, v54
	v_exp_f32_e32 v54, v55
	v_exp_f32_e32 v55, v57
	v_exp_f32_e32 v56, v56
	v_exp_f32_e32 v46, v58
	v_add_f32_e32 v48, v49, v54
	v_mul_f32_e32 v57, v146, v55
	v_add_f32_e32 v48, v56, v48
	v_mul_f32_e32 v58, 0.5, v57
	v_exp_f32_e32 v47, v59
	v_fma_f32 v59, v146, v48, v58
	s_nop 1
	v_add_f32_dpp v58, v58, v58 quad_perm:[1,0,3,2] row_mask:0xf bank_mask:0xf
	v_add_f32_dpp v59, v59, v59 quad_perm:[1,0,3,2] row_mask:0xf bank_mask:0xf
	s_nop 0
	v_add_f32_dpp v58, v58, v58 quad_perm:[2,3,0,1] row_mask:0xf bank_mask:0xf
	v_add_f32_dpp v59, v59, v59 quad_perm:[2,3,0,1] row_mask:0xf bank_mask:0xf
	s_nop 0
	v_add_f32_dpp v58, v58, v58 row_half_mirror row_mask:0xf bank_mask:0xf
	v_add_f32_dpp v59, v59, v59 row_half_mirror row_mask:0xf bank_mask:0xf
	s_and_saveexec_b64 s[20:21], s[4:5]
	ds_add_f32 v147, v59 offset:8
	ds_add_f32 v147, v58 offset:12
	s_or_b64 exec, exec, s[20:21]
	v_exp_f32_e32 v48, v52
	v_exp_f32_e32 v52, v53
	v_exp_f32_e32 v53, v60
	v_exp_f32_e32 v50, v50
	v_exp_f32_e32 v51, v51
	v_exp_f32_e32 v57, v61
	v_mul_f32_e32 v58, v146, v52
	v_add_f32_e32 v59, v46, v47
	v_add_f32_e32 v59, v48, v59
	v_mul_f32_e32 v60, 0.5, v58
	v_fma_f32 v59, v146, v59, v60
	s_nop 1
	v_add_f32_dpp v60, v60, v60 quad_perm:[1,0,3,2] row_mask:0xf bank_mask:0xf
	v_add_f32_dpp v59, v59, v59 quad_perm:[1,0,3,2] row_mask:0xf bank_mask:0xf
	s_nop 0
	v_add_f32_dpp v60, v60, v60 quad_perm:[2,3,0,1] row_mask:0xf bank_mask:0xf
	v_add_f32_dpp v59, v59, v59 quad_perm:[2,3,0,1] row_mask:0xf bank_mask:0xf
	s_nop 0
	v_add_f32_dpp v60, v60, v60 row_half_mirror row_mask:0xf bank_mask:0xf
	v_add_f32_dpp v59, v59, v59 row_half_mirror row_mask:0xf bank_mask:0xf
	s_and_saveexec_b64 s[20:21], s[4:5]
	ds_add_f32 v147, v59 offset:16
	ds_add_f32 v147, v60 offset:20
	s_or_b64 exec, exec, s[20:21]
	v_mul_f32_e32 v58, v146, v57
	v_add_f32_e32 v59, v50, v51
	v_add_f32_e32 v59, v53, v59
	v_mul_f32_e32 v60, 0.5, v58
	v_fma_f32 v59, v146, v59, v60
	s_nop 1
	v_add_f32_dpp v60, v60, v60 quad_perm:[1,0,3,2] row_mask:0xf bank_mask:0xf
	v_add_f32_dpp v59, v59, v59 quad_perm:[1,0,3,2] row_mask:0xf bank_mask:0xf
	s_nop 0
	v_add_f32_dpp v60, v60, v60 quad_perm:[2,3,0,1] row_mask:0xf bank_mask:0xf
	v_add_f32_dpp v59, v59, v59 quad_perm:[2,3,0,1] row_mask:0xf bank_mask:0xf
	s_nop 0
	v_add_f32_dpp v60, v60, v60 row_half_mirror row_mask:0xf bank_mask:0xf
	v_add_f32_dpp v59, v59, v59 row_half_mirror row_mask:0xf bank_mask:0xf
	s_and_saveexec_b64 s[20:21], s[4:5]
	ds_add_f32 v147, v59 offset:24
	ds_add_f32 v147, v60 offset:28
	s_or_b64 exec, exec, s[20:21]
	v_exp_f32_e32 v58, v142
	v_exp_f32_e32 v59, v145
	v_exp_f32_e32 v60, v143
	v_exp_f32_e32 v61, v144
	v_mul_f32_e32 v138, v146, v59
	v_add_f32_e32 v139, v58, v60
	v_add_f32_e32 v139, v61, v139
	v_mul_f32_e32 v140, 0.5, v138
	v_fma_f32 v139, v146, v139, v140
	s_nop 1
	v_add_f32_dpp v140, v140, v140 quad_perm:[1,0,3,2] row_mask:0xf bank_mask:0xf
	v_add_f32_dpp v139, v139, v139 quad_perm:[1,0,3,2] row_mask:0xf bank_mask:0xf
	s_nop 0
	v_add_f32_dpp v140, v140, v140 quad_perm:[2,3,0,1] row_mask:0xf bank_mask:0xf
	v_add_f32_dpp v139, v139, v139 quad_perm:[2,3,0,1] row_mask:0xf bank_mask:0xf
	s_nop 0
	v_add_f32_dpp v140, v140, v140 row_half_mirror row_mask:0xf bank_mask:0xf
	v_add_f32_dpp v139, v139, v139 row_half_mirror row_mask:0xf bank_mask:0xf
	s_and_saveexec_b64 s[20:21], s[4:5]
	ds_add_f32 v147, v139 offset:32
	ds_add_f32 v147, v140 offset:36
	s_or_b64 exec, exec, s[20:21]
	v_exp_f32_e32 v62, v62
	v_exp_f32_e32 v65, v65
	v_exp_f32_e32 v63, v63
	v_exp_f32_e32 v64, v64
	v_mul_f32_e32 v138, v146, v65
	v_add_f32_e32 v139, v62, v63
	v_add_f32_e32 v139, v64, v139
	v_mul_f32_e32 v140, 0.5, v138
	v_fma_f32 v139, v146, v139, v140
	s_nop 1
	v_add_f32_dpp v140, v140, v140 quad_perm:[1,0,3,2] row_mask:0xf bank_mask:0xf
	v_add_f32_dpp v139, v139, v139 quad_perm:[1,0,3,2] row_mask:0xf bank_mask:0xf
	s_nop 0
	v_add_f32_dpp v140, v140, v140 quad_perm:[2,3,0,1] row_mask:0xf bank_mask:0xf
	v_add_f32_dpp v139, v139, v139 quad_perm:[2,3,0,1] row_mask:0xf bank_mask:0xf
	s_nop 0
	v_add_f32_dpp v140, v140, v140 row_half_mirror row_mask:0xf bank_mask:0xf
	v_add_f32_dpp v139, v139, v139 row_half_mirror row_mask:0xf bank_mask:0xf
	s_and_saveexec_b64 s[20:21], s[4:5]
	ds_add_f32 v147, v139 offset:40
	ds_add_f32 v147, v140 offset:44
	s_or_b64 exec, exec, s[20:21]
	v_exp_f32_e32 v38, v38
	v_exp_f32_e32 v41, v41
	v_exp_f32_e32 v39, v39
	v_exp_f32_e32 v40, v40
	v_mul_f32_e32 v138, v146, v41
	v_add_f32_e32 v139, v38, v39
	v_add_f32_e32 v139, v40, v139
	v_mul_f32_e32 v140, 0.5, v138
	v_fma_f32 v139, v146, v139, v140
	s_nop 1
	v_add_f32_dpp v140, v140, v140 quad_perm:[1,0,3,2] row_mask:0xf bank_mask:0xf
	v_add_f32_dpp v139, v139, v139 quad_perm:[1,0,3,2] row_mask:0xf bank_mask:0xf
	s_nop 0
	v_add_f32_dpp v140, v140, v140 quad_perm:[2,3,0,1] row_mask:0xf bank_mask:0xf
	v_add_f32_dpp v139, v139, v139 quad_perm:[2,3,0,1] row_mask:0xf bank_mask:0xf
	s_nop 0
	v_add_f32_dpp v140, v140, v140 row_half_mirror row_mask:0xf bank_mask:0xf
	v_add_f32_dpp v139, v139, v139 row_half_mirror row_mask:0xf bank_mask:0xf
	s_and_saveexec_b64 s[20:21], s[4:5]
	ds_add_f32 v147, v139 offset:48
	ds_add_f32 v147, v140 offset:52
	s_or_b64 exec, exec, s[20:21]
	v_exp_f32_e32 v34, v34
	v_exp_f32_e32 v37, v37
	v_exp_f32_e32 v35, v35
	v_exp_f32_e32 v36, v36
	v_mul_f32_e32 v138, v146, v37
	v_add_f32_e32 v139, v34, v35
	v_add_f32_e32 v139, v36, v139
	v_mul_f32_e32 v140, 0.5, v138
	v_fma_f32 v139, v146, v139, v140
	s_nop 1
	v_add_f32_dpp v140, v140, v140 quad_perm:[1,0,3,2] row_mask:0xf bank_mask:0xf
	v_add_f32_dpp v139, v139, v139 quad_perm:[1,0,3,2] row_mask:0xf bank_mask:0xf
	s_nop 0
	v_add_f32_dpp v140, v140, v140 quad_perm:[2,3,0,1] row_mask:0xf bank_mask:0xf
	v_add_f32_dpp v139, v139, v139 quad_perm:[2,3,0,1] row_mask:0xf bank_mask:0xf
	s_nop 0
	v_add_f32_dpp v140, v140, v140 row_half_mirror row_mask:0xf bank_mask:0xf
	v_add_f32_dpp v139, v139, v139 row_half_mirror row_mask:0xf bank_mask:0xf
	s_and_saveexec_b64 s[20:21], s[4:5]
	ds_add_f32 v147, v139 offset:56
	ds_add_f32 v147, v140 offset:60
	s_or_b64 exec, exec, s[20:21]
	s_branch .LBB0_1946
